# P1 mix GEMM k-loops: rows kept as 32-bit offsets from the workspace base, loads use SGPR-base form, the 12 per-iteration 64-bit pointer advances and per-load 64-bit address adds replaced by four scala
# speedup vs baseline: 1.0094x; 1.0094x over previous
.LBB0_266:
	s_or_b64 exec, exec, s[28:29]
	s_and_b32 s3, s37, 0xffffff80
	v_or_b32_e32 v2, s3, v223
	v_ashrrev_i32_e32 v3, 31, v2
	v_lshlrev_b64 v[2:3], 11, v[2:3]
	v_lshl_add_u64 v[200:201], s[82:83], 0, v[2:3]
	v_or_b32_e32 v2, s3, v224
	v_ashrrev_i32_e32 v3, 31, v2
	v_lshlrev_b64 v[2:3], 11, v[2:3]
	v_lshl_add_u64 v[202:203], s[82:83], 0, v[2:3]
	v_or_b32_e32 v2, s3, v225
	v_ashrrev_i32_e32 v3, 31, v2
	v_lshlrev_b64 v[2:3], 11, v[2:3]
	v_lshl_add_u64 v[204:205], s[82:83], 0, v[2:3]
	v_or_b32_e32 v2, s3, v1
	s_mov_b32 s3, s21
	v_ashrrev_i32_e32 v3, 31, v2
	v_lshl_add_u64 v[208:209], v[186:187], 0, s[2:3]
	global_load_dwordx4 v[246:249], v[208:209], off
	global_load_dwordx4 v[250:253], v[208:209], off offset:-16
	s_add_u32 s2, s82, s20
	v_lshlrev_b64 v[2:3], 11, v[2:3]
	v_mov_b32_e32 v65, v172
	s_addc_u32 s3, s83, 0
	v_mov_b32_e32 v63, v172
	v_mov_b32_e32 v61, v172
	v_mov_b32_e32 v59, v172
	v_lshl_add_u64 v[206:207], s[82:83], 0, v[2:3]
	v_lshl_add_u64 v[210:211], s[2:3], 0, v[64:65]
	v_lshl_add_u64 v[212:213], s[2:3], 0, v[62:63]
	v_lshl_add_u64 v[214:215], s[2:3], 0, v[60:61]
	v_lshl_add_u64 v[216:217], s[2:3], 0, v[58:59]
	s_mov_b32 s20, 0
	v_mov_b32_e32 v51, v50
	v_mov_b32_e32 v52, v50
	v_mov_b32_e32 v53, v50
	v_mov_b32_e32 v54, v50
	v_mov_b32_e32 v55, v50
	v_mov_b32_e32 v56, v50
	v_mov_b32_e32 v57, v50
	v_mov_b32_e32 v58, v50
	v_mov_b32_e32 v59, v50
	v_mov_b32_e32 v60, v50
	v_mov_b32_e32 v61, v50
	v_mov_b32_e32 v62, v50
	v_mov_b32_e32 v63, v50
	v_mov_b32_e32 v64, v50
	v_mov_b32_e32 v65, v50
	v_mov_b32_e32 v34, v50
	v_mov_b32_e32 v35, v50
	v_mov_b32_e32 v36, v50
	v_mov_b32_e32 v37, v50
	v_mov_b32_e32 v38, v50
	v_mov_b32_e32 v39, v50
	v_mov_b32_e32 v40, v50
	v_mov_b32_e32 v41, v50
	v_mov_b32_e32 v42, v50
	v_mov_b32_e32 v43, v50
	v_mov_b32_e32 v44, v50
	v_mov_b32_e32 v45, v50
	v_mov_b32_e32 v46, v50
	v_mov_b32_e32 v47, v50
	v_mov_b32_e32 v48, v50
	v_mov_b32_e32 v49, v50
	v_mov_b32_e32 v18, v50
	v_mov_b32_e32 v19, v50
	v_mov_b32_e32 v20, v50
	v_mov_b32_e32 v21, v50
	v_mov_b32_e32 v22, v50
	v_mov_b32_e32 v23, v50
	v_mov_b32_e32 v24, v50
	v_mov_b32_e32 v25, v50
	v_mov_b32_e32 v26, v50
	v_mov_b32_e32 v27, v50
	v_mov_b32_e32 v28, v50
	v_mov_b32_e32 v29, v50
	v_mov_b32_e32 v30, v50
	v_mov_b32_e32 v31, v50
	v_mov_b32_e32 v32, v50
	v_mov_b32_e32 v33, v50
	v_mov_b32_e32 v2, v50
	v_mov_b32_e32 v3, v50
	v_mov_b32_e32 v4, v50
	v_mov_b32_e32 v5, v50
	v_mov_b32_e32 v6, v50
	v_mov_b32_e32 v7, v50
	v_mov_b32_e32 v8, v50
	v_mov_b32_e32 v9, v50
	v_mov_b32_e32 v10, v50
	v_mov_b32_e32 v11, v50
	v_mov_b32_e32 v12, v50
	v_mov_b32_e32 v13, v50
	v_mov_b32_e32 v14, v50
	v_mov_b32_e32 v15, v50
	v_mov_b32_e32 v16, v50
	v_mov_b32_e32 v17, v50
	s_waitcnt lgkmcnt(0)
	s_barrier
	s_waitcnt vmcnt(0)
	v_subrev_u32_e32 v206, s82, v206
	v_add_u32_e32 v206, v206, v188
	v_subrev_u32_e32 v192, s82, v192
	v_add_u32_e32 v192, v192, v188
	v_subrev_u32_e32 v216, s82, v216
	v_add_u32_e32 v216, v216, v188
	v_subrev_u32_e32 v204, s82, v204
	v_add_u32_e32 v204, v204, v188
	v_subrev_u32_e32 v194, s82, v194
	v_add_u32_e32 v194, v194, v188
	v_subrev_u32_e32 v214, s82, v214
	v_add_u32_e32 v214, v214, v188
	v_subrev_u32_e32 v202, s82, v202
	v_add_u32_e32 v202, v202, v188
	v_subrev_u32_e32 v196, s82, v196
	v_add_u32_e32 v196, v196, v188
	v_subrev_u32_e32 v212, s82, v212
	v_add_u32_e32 v212, v212, v188
	v_subrev_u32_e32 v200, s82, v200
	v_add_u32_e32 v200, v200, v188
	v_subrev_u32_e32 v198, s82, v198
	v_add_u32_e32 v198, v198, v188
	v_subrev_u32_e32 v210, s82, v210
	v_add_u32_e32 v210, v210, v188
	s_add_u32 s84, s82, 0xa380000
	s_addc_u32 s85, s83, 0
	s_mov_b32 s86, s82
	s_mov_b32 s87, s83
	s_branch .LBB0_269

.LBB0_268:
	ds_read_b128 v[162:165], v227 offset:36864
	ds_read_b128 v[166:169], v228 offset:55296
	ds_read_b128 v[230:233], v228 offset:59904
	s_mov_b64 s[28:29], 0x200
	s_add_i32 s20, s20, 2
	v_lshl_add_u64 v[208:209], v[208:209], 0, s[28:29]
	s_waitcnt lgkmcnt(1)
	v_mfma_f32_32x32x16_bf16 v[50:65], v[162:165], v[166:169], v[50:65]
	s_add_u32 s84, s84, s22
	s_addc_u32 s85, s85, s23
	s_add_u32 s86, s86, s22
	s_addc_u32 s87, s87, s23
	s_waitcnt lgkmcnt(0)
	v_mfma_f32_32x32x16_bf16 v[34:49], v[162:165], v[230:233], v[34:49]
	ds_read_b128 v[162:165], v227 offset:41472
	s_andn2_b64 vcc, exec, s[2:3]
	s_waitcnt lgkmcnt(0)
	v_mfma_f32_32x32x16_bf16 v[18:33], v[162:165], v[166:169], v[18:33]
	v_mfma_f32_32x32x16_bf16 v[2:17], v[162:165], v[230:233], v[2:17]
	ds_read_b128 v[162:165], v227 offset:36896
	ds_read_b128 v[166:169], v228 offset:55328
	ds_read_b128 v[230:233], v228 offset:59936
	s_waitcnt lgkmcnt(1)
	v_mfma_f32_32x32x16_bf16 v[50:65], v[162:165], v[166:169], v[50:65]
	s_waitcnt lgkmcnt(0)
	v_mfma_f32_32x32x16_bf16 v[34:49], v[162:165], v[230:233], v[34:49]
	ds_read_b128 v[162:165], v227 offset:41504
	s_waitcnt lgkmcnt(0)
	v_mfma_f32_32x32x16_bf16 v[18:33], v[162:165], v[166:169], v[18:33]
	v_mfma_f32_32x32x16_bf16 v[2:17], v[162:165], v[230:233], v[2:17]
	ds_read_b128 v[162:165], v227 offset:36928
	ds_read_b128 v[166:169], v228 offset:55360
	ds_read_b128 v[230:233], v228 offset:59968
	s_waitcnt lgkmcnt(1)
	v_mfma_f32_32x32x16_bf16 v[50:65], v[162:165], v[166:169], v[50:65]
	s_waitcnt lgkmcnt(0)
	v_mfma_f32_32x32x16_bf16 v[34:49], v[162:165], v[230:233], v[34:49]
	ds_read_b128 v[162:165], v227 offset:41536
	s_waitcnt lgkmcnt(0)
	v_mfma_f32_32x32x16_bf16 v[18:33], v[162:165], v[166:169], v[18:33]
	v_mfma_f32_32x32x16_bf16 v[2:17], v[162:165], v[230:233], v[2:17]
	ds_read_b128 v[162:165], v227 offset:36960
	ds_read_b128 v[166:169], v228 offset:55392
	ds_read_b128 v[230:233], v227 offset:41568
	ds_read_b128 v[234:237], v228 offset:60000
	s_waitcnt lgkmcnt(0)
	s_barrier
	v_mfma_f32_32x32x16_bf16 v[50:65], v[162:165], v[166:169], v[50:65]
	v_mfma_f32_32x32x16_bf16 v[34:49], v[162:165], v[234:237], v[34:49]
	v_mfma_f32_32x32x16_bf16 v[18:33], v[230:233], v[166:169], v[18:33]
	v_mfma_f32_32x32x16_bf16 v[2:17], v[230:233], v[234:237], v[2:17]
	s_cbranch_vccz .LBB0_289
.LBB0_269:
	s_waitcnt vmcnt(8)
	v_lshlrev_b32_e32 v230, 16, v66
	v_and_b32_e32 v231, 0xffff0000, v66
	v_lshlrev_b32_e32 v232, 16, v70
	v_and_b32_e32 v233, 0xffff0000, v70
	v_pk_add_f32 v[232:233], v[232:233], v[230:231] neg_lo:[0,1] neg_hi:[0,1]
	v_lshlrev_b32_e32 v234, 16, v71
	v_and_b32_e32 v235, 0xffff0000, v71
	v_lshlrev_b32_e32 v236, 16, v73
	v_and_b32_e32 v237, 0xffff0000, v73
	s_cmp_gt_u32 s20, 12
	v_pk_fma_f32 v[230:231], v[232:233], v[250:251], v[230:231]
	v_lshlrev_b32_e32 v232, 16, v67
	v_and_b32_e32 v233, 0xffff0000, v67
	v_pk_add_f32 v[234:235], v[234:235], v[232:233] neg_lo:[0,1] neg_hi:[0,1]
	v_cvt_pk_bf16_f32 v230, v230, v231
	v_pk_fma_f32 v[232:233], v[234:235], v[252:253], v[232:233]
	v_lshlrev_b32_e32 v234, 16, v72
	v_cvt_pk_bf16_f32 v231, v232, v233
	v_lshlrev_b32_e32 v232, 16, v68
	v_and_b32_e32 v233, 0xffff0000, v68
	v_and_b32_e32 v235, 0xffff0000, v72
	v_pk_add_f32 v[234:235], v[234:235], v[232:233] neg_lo:[0,1] neg_hi:[0,1]
	s_nop 0
	v_pk_fma_f32 v[232:233], v[234:235], v[246:247], v[232:233]
	v_lshlrev_b32_e32 v234, 16, v69
	v_and_b32_e32 v235, 0xffff0000, v69
	v_pk_add_f32 v[236:237], v[236:237], v[234:235] neg_lo:[0,1] neg_hi:[0,1]
	v_cvt_pk_bf16_f32 v232, v232, v233
	v_pk_fma_f32 v[234:235], v[236:237], v[248:249], v[234:235]
	v_lshlrev_b32_e32 v236, 16, v89
	v_cvt_pk_bf16_f32 v233, v234, v235
	ds_write_b128 v219, v[230:233] offset:36864
	ds_write_b128 v219, v[74:77] offset:55296
	v_lshlrev_b32_e32 v230, 16, v82
	v_and_b32_e32 v231, 0xffff0000, v82
	v_lshlrev_b32_e32 v232, 16, v86
	v_and_b32_e32 v233, 0xffff0000, v86
	v_pk_add_f32 v[232:233], v[232:233], v[230:231] neg_lo:[0,1] neg_hi:[0,1]
	v_lshlrev_b32_e32 v234, 16, v87
	v_pk_fma_f32 v[230:231], v[232:233], v[250:251], v[230:231]
	v_lshlrev_b32_e32 v232, 16, v83
	v_and_b32_e32 v233, 0xffff0000, v83
	v_and_b32_e32 v235, 0xffff0000, v87
	v_pk_add_f32 v[234:235], v[234:235], v[232:233] neg_lo:[0,1] neg_hi:[0,1]
	v_cvt_pk_bf16_f32 v230, v230, v231
	v_pk_fma_f32 v[232:233], v[234:235], v[252:253], v[232:233]
	v_lshlrev_b32_e32 v234, 16, v88
	v_cvt_pk_bf16_f32 v231, v232, v233
	v_lshlrev_b32_e32 v232, 16, v84
	v_and_b32_e32 v233, 0xffff0000, v84
	v_and_b32_e32 v235, 0xffff0000, v88
	v_pk_add_f32 v[234:235], v[234:235], v[232:233] neg_lo:[0,1] neg_hi:[0,1]
	v_and_b32_e32 v237, 0xffff0000, v89
	v_pk_fma_f32 v[232:233], v[234:235], v[246:247], v[232:233]
	v_lshlrev_b32_e32 v234, 16, v85
	v_and_b32_e32 v235, 0xffff0000, v85
	v_pk_add_f32 v[236:237], v[236:237], v[234:235] neg_lo:[0,1] neg_hi:[0,1]
	v_cvt_pk_bf16_f32 v232, v232, v233
	v_pk_fma_f32 v[234:235], v[236:237], v[248:249], v[234:235]
	v_lshlrev_b32_e32 v236, 16, v97
	v_cvt_pk_bf16_f32 v233, v234, v235
	ds_write_b128 v219, v[230:233] offset:41472
	ds_write_b128 v219, v[78:81] offset:59904
	v_lshlrev_b32_e32 v230, 16, v90
	v_and_b32_e32 v231, 0xffff0000, v90
	v_lshlrev_b32_e32 v232, 16, v94
	v_and_b32_e32 v233, 0xffff0000, v94
	v_pk_add_f32 v[232:233], v[232:233], v[230:231] neg_lo:[0,1] neg_hi:[0,1]
	v_lshlrev_b32_e32 v234, 16, v95
	v_pk_fma_f32 v[230:231], v[232:233], v[250:251], v[230:231]
	v_lshlrev_b32_e32 v232, 16, v91
	v_and_b32_e32 v233, 0xffff0000, v91
	v_and_b32_e32 v235, 0xffff0000, v95
	v_pk_add_f32 v[234:235], v[234:235], v[232:233] neg_lo:[0,1] neg_hi:[0,1]
	v_cvt_pk_bf16_f32 v230, v230, v231
	v_pk_fma_f32 v[232:233], v[234:235], v[252:253], v[232:233]
	v_lshlrev_b32_e32 v234, 16, v96
	v_cvt_pk_bf16_f32 v231, v232, v233
	v_lshlrev_b32_e32 v232, 16, v92
	v_and_b32_e32 v233, 0xffff0000, v92
	v_and_b32_e32 v235, 0xffff0000, v96
	v_pk_add_f32 v[234:235], v[234:235], v[232:233] neg_lo:[0,1] neg_hi:[0,1]
	v_and_b32_e32 v237, 0xffff0000, v97
	v_pk_fma_f32 v[232:233], v[234:235], v[246:247], v[232:233]
	v_lshlrev_b32_e32 v234, 16, v93
	v_and_b32_e32 v235, 0xffff0000, v93
	v_pk_add_f32 v[236:237], v[236:237], v[234:235] neg_lo:[0,1] neg_hi:[0,1]
	v_cvt_pk_bf16_f32 v232, v232, v233
	v_pk_fma_f32 v[234:235], v[236:237], v[248:249], v[234:235]
	s_nop 0
	v_cvt_pk_bf16_f32 v233, v234, v235
	ds_write_b128 v219, v[230:233] offset:46080
	ds_write_b128 v219, v[98:101] offset:64512
	v_lshlrev_b32_e32 v230, 16, v102
	v_and_b32_e32 v231, 0xffff0000, v102
	v_lshlrev_b32_e32 v232, 16, v106
	v_and_b32_e32 v233, 0xffff0000, v106
	v_pk_add_f32 v[232:233], v[232:233], v[230:231] neg_lo:[0,1] neg_hi:[0,1]
	s_nop 0
	v_pk_fma_f32 v[166:167], v[232:233], v[250:251], v[230:231]
	v_lshlrev_b32_e32 v230, 16, v103
	v_and_b32_e32 v231, 0xffff0000, v103
	v_lshlrev_b32_e32 v232, 16, v107
	v_and_b32_e32 v233, 0xffff0000, v107
	v_pk_add_f32 v[232:233], v[232:233], v[230:231] neg_lo:[0,1] neg_hi:[0,1]
	v_cvt_pk_bf16_f32 v166, v166, v167
	v_pk_fma_f32 v[168:169], v[232:233], v[252:253], v[230:231]
	v_lshlrev_b32_e32 v230, 16, v108
	v_cvt_pk_bf16_f32 v167, v168, v169
	v_lshlrev_b32_e32 v168, 16, v104
	v_and_b32_e32 v169, 0xffff0000, v104
	v_and_b32_e32 v231, 0xffff0000, v108
	v_pk_add_f32 v[230:231], v[230:231], v[168:169] neg_lo:[0,1] neg_hi:[0,1]
	s_nop 0
	v_pk_fma_f32 v[162:163], v[230:231], v[246:247], v[168:169]
	v_lshlrev_b32_e32 v230, 16, v109
	v_cvt_pk_bf16_f32 v168, v162, v163
	v_lshlrev_b32_e32 v162, 16, v105
	v_and_b32_e32 v163, 0xffff0000, v105
	v_and_b32_e32 v231, 0xffff0000, v109
	v_pk_add_f32 v[230:231], v[230:231], v[162:163] neg_lo:[0,1] neg_hi:[0,1]
	s_nop 0
	v_pk_fma_f32 v[162:163], v[230:231], v[248:249], v[162:163]
	s_nop 0
	v_cvt_pk_bf16_f32 v169, v162, v163
	ds_write_b128 v219, v[166:169] offset:50688
	ds_write_b128 v221, v[110:113] offset:13824
	s_cbranch_scc1 .LBB0_279
	global_load_dwordx4 v[246:249], v[208:209], off offset:256
	global_load_dwordx4 v[250:253], v[208:209], off offset:240
	s_nop 0
	global_load_dwordx4 v[66:69], v206, s[84:85] offset:384
	v_mov_b32_e32 v80, 0
	global_load_dwordx4 v[70:73], v192, s[86:87] offset:384
	v_mov_b32_e32 v81, v172
	v_mov_b64_e32 v[76:77], v[80:81]
	v_mov_b64_e32 v[74:75], v[80:81]
	s_and_saveexec_b64 s[2:3], s[4:5]
	s_cbranch_execz .LBB0_272
	global_load_dwordx4 v[74:77], v216, s[86:87] offset:384
.LBB0_272:
	s_or_b64 exec, exec, s[2:3]
	s_nop 1
	global_load_dwordx4 v[82:85], v204, s[84:85] offset:384
	global_load_dwordx4 v[86:89], v194, s[86:87] offset:384
	v_mov_b64_e32 v[78:79], v[80:81]
	s_and_saveexec_b64 s[2:3], s[6:7]
	s_cbranch_execz .LBB0_274
	global_load_dwordx4 v[78:81], v214, s[86:87] offset:384
.LBB0_274:
	s_or_b64 exec, exec, s[2:3]
	s_nop 0
	global_load_dwordx4 v[90:93], v202, s[84:85] offset:384
	v_mov_b32_e32 v173, v172
	global_load_dwordx4 v[94:97], v196, s[86:87] offset:384
	v_mov_b64_e32 v[100:101], v[172:173]
	v_mov_b64_e32 v[98:99], v[172:173]
	s_and_saveexec_b64 s[2:3], s[8:9]
	s_cbranch_execz .LBB0_276
	global_load_dwordx4 v[98:101], v212, s[86:87] offset:384
.LBB0_276:
	s_or_b64 exec, exec, s[2:3]
	s_nop 0
	global_load_dwordx4 v[102:105], v200, s[84:85] offset:384
	v_mov_b32_e32 v111, 0
	global_load_dwordx4 v[106:109], v198, s[86:87] offset:384
	v_mov_b32_e32 v110, 0
	v_mov_b32_e32 v113, 0
	v_mov_b32_e32 v112, 0
	s_and_saveexec_b64 s[2:3], s[10:11]
	s_cbranch_execz .LBB0_278
	global_load_dwordx4 v[110:113], v210, s[86:87] offset:384

.LBB0_279:
	ds_read_b128 v[162:165], v227
	ds_read_b128 v[166:169], v228 offset:18432
	ds_read_b128 v[230:233], v228 offset:23040
	s_cmp_gt_u32 s20, 13
	s_cselect_b64 s[2:3], -1, 0
	s_and_b64 vcc, exec, s[2:3]
	s_waitcnt lgkmcnt(1)
	v_mfma_f32_32x32x16_bf16 v[50:65], v[162:165], v[166:169], v[50:65]
	s_waitcnt lgkmcnt(0)
	v_mfma_f32_32x32x16_bf16 v[34:49], v[162:165], v[230:233], v[34:49]
	ds_read_b128 v[162:165], v227 offset:4608
	s_waitcnt lgkmcnt(0)
	v_mfma_f32_32x32x16_bf16 v[18:33], v[162:165], v[166:169], v[18:33]
	v_mfma_f32_32x32x16_bf16 v[2:17], v[162:165], v[230:233], v[2:17]
	ds_read_b128 v[162:165], v227 offset:32
	ds_read_b128 v[166:169], v228 offset:18464
	ds_read_b128 v[230:233], v228 offset:23072
	s_waitcnt lgkmcnt(1)
	v_mfma_f32_32x32x16_bf16 v[50:65], v[162:165], v[166:169], v[50:65]
	s_waitcnt lgkmcnt(0)
	v_mfma_f32_32x32x16_bf16 v[34:49], v[162:165], v[230:233], v[34:49]
	ds_read_b128 v[162:165], v227 offset:4640
	s_waitcnt lgkmcnt(0)
	v_mfma_f32_32x32x16_bf16 v[18:33], v[162:165], v[166:169], v[18:33]
	v_mfma_f32_32x32x16_bf16 v[2:17], v[162:165], v[230:233], v[2:17]
	ds_read_b128 v[162:165], v227 offset:64
	ds_read_b128 v[166:169], v228 offset:18496
	ds_read_b128 v[230:233], v228 offset:23104
	s_waitcnt lgkmcnt(1)
	v_mfma_f32_32x32x16_bf16 v[50:65], v[162:165], v[166:169], v[50:65]
	s_waitcnt lgkmcnt(0)
	v_mfma_f32_32x32x16_bf16 v[34:49], v[162:165], v[230:233], v[34:49]
	ds_read_b128 v[162:165], v227 offset:4672
	s_waitcnt lgkmcnt(0)
	v_mfma_f32_32x32x16_bf16 v[18:33], v[162:165], v[166:169], v[18:33]
	v_mfma_f32_32x32x16_bf16 v[2:17], v[162:165], v[230:233], v[2:17]
	ds_read_b128 v[162:165], v227 offset:96
	ds_read_b128 v[166:169], v228 offset:18528
	ds_read_b128 v[230:233], v228 offset:23136
	s_waitcnt lgkmcnt(1)
	v_mfma_f32_32x32x16_bf16 v[50:65], v[162:165], v[166:169], v[50:65]
	s_waitcnt lgkmcnt(0)
	v_mfma_f32_32x32x16_bf16 v[34:49], v[162:165], v[230:233], v[34:49]
	ds_read_b128 v[162:165], v227 offset:4704
	s_waitcnt lgkmcnt(0)
	s_barrier
	v_mfma_f32_32x32x16_bf16 v[18:33], v[162:165], v[166:169], v[18:33]
	v_mfma_f32_32x32x16_bf16 v[2:17], v[162:165], v[230:233], v[2:17]
	s_cbranch_vccnz .LBB0_268
	s_waitcnt vmcnt(8)
	v_lshlrev_b32_e32 v230, 16, v114
	v_and_b32_e32 v231, 0xffff0000, v114
	v_lshlrev_b32_e32 v232, 16, v118
	v_and_b32_e32 v233, 0xffff0000, v118
	v_pk_add_f32 v[232:233], v[232:233], v[230:231] neg_lo:[0,1] neg_hi:[0,1]
	v_lshlrev_b32_e32 v234, 16, v119
	v_and_b32_e32 v235, 0xffff0000, v119
	v_lshlrev_b32_e32 v236, 16, v121
	v_and_b32_e32 v237, 0xffff0000, v121
	s_cmp_gt_u32 s20, 11
	v_pk_fma_f32 v[230:231], v[232:233], v[250:251], v[230:231]
	v_lshlrev_b32_e32 v232, 16, v115
	v_and_b32_e32 v233, 0xffff0000, v115
	v_pk_add_f32 v[234:235], v[234:235], v[232:233] neg_lo:[0,1] neg_hi:[0,1]
	v_cvt_pk_bf16_f32 v230, v230, v231
	v_pk_fma_f32 v[232:233], v[234:235], v[252:253], v[232:233]
	v_lshlrev_b32_e32 v234, 16, v120
	v_cvt_pk_bf16_f32 v231, v232, v233
	v_lshlrev_b32_e32 v232, 16, v116
	v_and_b32_e32 v233, 0xffff0000, v116
	v_and_b32_e32 v235, 0xffff0000, v120
	v_pk_add_f32 v[234:235], v[234:235], v[232:233] neg_lo:[0,1] neg_hi:[0,1]
	s_nop 0
	v_pk_fma_f32 v[232:233], v[234:235], v[246:247], v[232:233]
	v_lshlrev_b32_e32 v234, 16, v117
	v_and_b32_e32 v235, 0xffff0000, v117
	v_pk_add_f32 v[236:237], v[236:237], v[234:235] neg_lo:[0,1] neg_hi:[0,1]
	v_cvt_pk_bf16_f32 v232, v232, v233
	v_pk_fma_f32 v[234:235], v[236:237], v[248:249], v[234:235]
	v_lshlrev_b32_e32 v236, 16, v137
	v_cvt_pk_bf16_f32 v233, v234, v235
	ds_write_b128 v219, v[230:233]
	ds_write_b128 v219, v[122:125] offset:18432
	v_lshlrev_b32_e32 v230, 16, v130
	v_and_b32_e32 v231, 0xffff0000, v130
	v_lshlrev_b32_e32 v232, 16, v134
	v_and_b32_e32 v233, 0xffff0000, v134
	v_pk_add_f32 v[232:233], v[232:233], v[230:231] neg_lo:[0,1] neg_hi:[0,1]
	v_lshlrev_b32_e32 v234, 16, v135
	v_pk_fma_f32 v[230:231], v[232:233], v[250:251], v[230:231]
	v_lshlrev_b32_e32 v232, 16, v131
	v_and_b32_e32 v233, 0xffff0000, v131
	v_and_b32_e32 v235, 0xffff0000, v135
	v_pk_add_f32 v[234:235], v[234:235], v[232:233] neg_lo:[0,1] neg_hi:[0,1]
	v_cvt_pk_bf16_f32 v230, v230, v231
	v_pk_fma_f32 v[232:233], v[234:235], v[252:253], v[232:233]
	v_lshlrev_b32_e32 v234, 16, v136
	v_cvt_pk_bf16_f32 v231, v232, v233
	v_lshlrev_b32_e32 v232, 16, v132
	v_and_b32_e32 v233, 0xffff0000, v132
	v_and_b32_e32 v235, 0xffff0000, v136
	v_pk_add_f32 v[234:235], v[234:235], v[232:233] neg_lo:[0,1] neg_hi:[0,1]
	v_and_b32_e32 v237, 0xffff0000, v137
	v_pk_fma_f32 v[232:233], v[234:235], v[246:247], v[232:233]
	v_lshlrev_b32_e32 v234, 16, v133
	v_and_b32_e32 v235, 0xffff0000, v133
	v_pk_add_f32 v[236:237], v[236:237], v[234:235] neg_lo:[0,1] neg_hi:[0,1]
	v_cvt_pk_bf16_f32 v232, v232, v233
	v_pk_fma_f32 v[234:235], v[236:237], v[248:249], v[234:235]
	v_lshlrev_b32_e32 v236, 16, v145
	v_cvt_pk_bf16_f32 v233, v234, v235
	ds_write_b128 v219, v[230:233] offset:4608
	ds_write_b128 v219, v[126:129] offset:23040
	v_lshlrev_b32_e32 v230, 16, v138
	v_and_b32_e32 v231, 0xffff0000, v138
	v_lshlrev_b32_e32 v232, 16, v142
	v_and_b32_e32 v233, 0xffff0000, v142
	v_pk_add_f32 v[232:233], v[232:233], v[230:231] neg_lo:[0,1] neg_hi:[0,1]
	v_lshlrev_b32_e32 v234, 16, v143
	v_pk_fma_f32 v[230:231], v[232:233], v[250:251], v[230:231]
	v_lshlrev_b32_e32 v232, 16, v139
	v_and_b32_e32 v233, 0xffff0000, v139
	v_and_b32_e32 v235, 0xffff0000, v143
	v_pk_add_f32 v[234:235], v[234:235], v[232:233] neg_lo:[0,1] neg_hi:[0,1]
	v_cvt_pk_bf16_f32 v230, v230, v231
	v_pk_fma_f32 v[232:233], v[234:235], v[252:253], v[232:233]
	v_lshlrev_b32_e32 v234, 16, v144
	v_cvt_pk_bf16_f32 v231, v232, v233
	v_lshlrev_b32_e32 v232, 16, v140
	v_and_b32_e32 v233, 0xffff0000, v140
	v_and_b32_e32 v235, 0xffff0000, v144
	v_pk_add_f32 v[234:235], v[234:235], v[232:233] neg_lo:[0,1] neg_hi:[0,1]
	v_and_b32_e32 v237, 0xffff0000, v145
	v_pk_fma_f32 v[232:233], v[234:235], v[246:247], v[232:233]
	v_lshlrev_b32_e32 v234, 16, v141
	v_and_b32_e32 v235, 0xffff0000, v141
	v_pk_add_f32 v[236:237], v[236:237], v[234:235] neg_lo:[0,1] neg_hi:[0,1]
	v_cvt_pk_bf16_f32 v232, v232, v233
	v_pk_fma_f32 v[234:235], v[236:237], v[248:249], v[234:235]
	s_nop 0
	v_cvt_pk_bf16_f32 v233, v234, v235
	ds_write_b128 v219, v[230:233] offset:9216
	ds_write_b128 v219, v[146:149] offset:27648
	v_lshlrev_b32_e32 v230, 16, v150
	v_and_b32_e32 v231, 0xffff0000, v150
	v_lshlrev_b32_e32 v232, 16, v154
	v_and_b32_e32 v233, 0xffff0000, v154
	v_pk_add_f32 v[232:233], v[232:233], v[230:231] neg_lo:[0,1] neg_hi:[0,1]
	s_nop 0
	v_pk_fma_f32 v[166:167], v[232:233], v[250:251], v[230:231]
	v_lshlrev_b32_e32 v230, 16, v151
	v_and_b32_e32 v231, 0xffff0000, v151
	v_lshlrev_b32_e32 v232, 16, v155
	v_and_b32_e32 v233, 0xffff0000, v155
	v_pk_add_f32 v[232:233], v[232:233], v[230:231] neg_lo:[0,1] neg_hi:[0,1]
	v_cvt_pk_bf16_f32 v166, v166, v167
	v_pk_fma_f32 v[168:169], v[232:233], v[252:253], v[230:231]
	v_lshlrev_b32_e32 v230, 16, v156
	v_cvt_pk_bf16_f32 v167, v168, v169
	v_lshlrev_b32_e32 v168, 16, v152
	v_and_b32_e32 v169, 0xffff0000, v152
	v_and_b32_e32 v231, 0xffff0000, v156
	v_pk_add_f32 v[230:231], v[230:231], v[168:169] neg_lo:[0,1] neg_hi:[0,1]
	s_nop 0
	v_pk_fma_f32 v[162:163], v[230:231], v[246:247], v[168:169]
	v_lshlrev_b32_e32 v230, 16, v157
	v_cvt_pk_bf16_f32 v168, v162, v163
	v_lshlrev_b32_e32 v162, 16, v153
	v_and_b32_e32 v163, 0xffff0000, v153
	v_and_b32_e32 v231, 0xffff0000, v157
	v_pk_add_f32 v[230:231], v[230:231], v[162:163] neg_lo:[0,1] neg_hi:[0,1]
	s_nop 0
	v_pk_fma_f32 v[162:163], v[230:231], v[248:249], v[162:163]
	s_nop 0
	v_cvt_pk_bf16_f32 v169, v162, v163
	ds_write_b128 v219, v[166:169] offset:13824
	ds_write_b128 v219, v[158:161] offset:32256
	global_load_dwordx4 v[246:249], v[208:209], off offset:512
	global_load_dwordx4 v[250:253], v[208:209], off offset:496
	s_cbranch_scc1 .Lmixpf_a_last
	s_nop 0
	global_load_dwordx4 v[114:117], v206, s[84:85] offset:512
	v_mov_b32_e32 v128, 0
	global_load_dwordx4 v[118:121], v192, s[86:87] offset:512
	v_mov_b32_e32 v129, v172
	v_mov_b64_e32 v[124:125], v[128:129]
	v_mov_b64_e32 v[122:123], v[128:129]
	s_and_saveexec_b64 s[28:29], s[4:5]
	s_cbranch_execz .LBB0_283
	global_load_dwordx4 v[122:125], v216, s[86:87] offset:512
.LBB0_283:
	s_or_b64 exec, exec, s[28:29]
	s_nop 1
	global_load_dwordx4 v[130:133], v204, s[84:85] offset:512
	global_load_dwordx4 v[134:137], v194, s[86:87] offset:512
	v_mov_b64_e32 v[126:127], v[128:129]
	s_and_saveexec_b64 s[28:29], s[6:7]
	s_cbranch_execz .LBB0_285
	global_load_dwordx4 v[126:129], v214, s[86:87] offset:512
.LBB0_285:
	s_or_b64 exec, exec, s[28:29]
	s_nop 0
	global_load_dwordx4 v[138:141], v202, s[84:85] offset:512
	v_mov_b32_e32 v173, v172
	global_load_dwordx4 v[142:145], v196, s[86:87] offset:512
	v_mov_b64_e32 v[148:149], v[172:173]
	v_mov_b64_e32 v[146:147], v[172:173]
	s_and_saveexec_b64 s[28:29], s[8:9]
	s_cbranch_execz .LBB0_287
	global_load_dwordx4 v[146:149], v212, s[86:87] offset:512
.LBB0_287:
	s_or_b64 exec, exec, s[28:29]
	s_nop 0
	global_load_dwordx4 v[150:153], v200, s[84:85] offset:512
	v_mov_b32_e32 v159, 0
	global_load_dwordx4 v[154:157], v198, s[86:87] offset:512
	v_mov_b32_e32 v158, 0
	v_mov_b32_e32 v161, 0
	v_mov_b32_e32 v160, 0
	s_and_saveexec_b64 s[28:29], s[10:11]
	s_cbranch_execz .LBB0_267
	global_load_dwordx4 v[158:161], v210, s[86:87] offset:512
	s_branch .LBB0_267

.LBB0_672:
	s_or_b64 exec, exec, s[22:23]
	s_lshl_b32 s22, s28, 11
	s_and_b32 s22, s22, 0x1c0000
	s_add_u32 s2, s26, s2
	v_lshl_or_b32 v4, v171, 1, s22
	v_mov_b32_e32 v5, v172
	v_mov_b32_e32 v165, v172
	s_addc_u32 s3, s27, s3
	v_mov_b32_e32 v163, v172
	v_mov_b32_e32 v63, v172
	v_lshl_add_u64 v[194:195], v[178:179], 0, s[14:15]
	global_load_dwordx4 v[246:249], v[194:195], off
	global_load_dwordx4 v[250:253], v[194:195], off offset:-16
	v_lshl_add_u64 v[196:197], s[2:3], 0, v[164:165]
	v_lshl_add_u64 v[198:199], s[82:83], 0, v[166:167]
	v_lshl_add_u64 v[200:201], s[82:83], 0, v[60:61]
	v_lshl_add_u64 v[202:203], s[2:3], 0, v[162:163]
	v_lshl_add_u64 v[204:205], s[82:83], 0, v[64:65]
	v_lshl_add_u64 v[206:207], s[2:3], 0, v[62:63]
	v_lshl_add_u64 v[208:209], s[82:83], 0, v[58:59]
	v_lshl_add_u64 v[210:211], s[2:3], 0, v[4:5]
	s_mov_b32 s14, 0
	v_mov_b32_e32 v3, v2
	v_mov_b32_e32 v4, v2
	v_mov_b32_e32 v5, v2
	v_mov_b32_e32 v6, v2
	v_mov_b32_e32 v7, v2
	v_mov_b32_e32 v8, v2
	v_mov_b32_e32 v9, v2
	v_mov_b32_e32 v10, v2
	v_mov_b32_e32 v11, v2
	v_mov_b32_e32 v12, v2
	v_mov_b32_e32 v13, v2
	v_mov_b32_e32 v14, v2
	v_mov_b32_e32 v15, v2
	v_mov_b32_e32 v16, v2
	v_mov_b32_e32 v17, v2
	v_mov_b32_e32 v18, v2
	v_mov_b32_e32 v19, v2
	v_mov_b32_e32 v20, v2
	v_mov_b32_e32 v21, v2
	v_mov_b32_e32 v22, v2
	v_mov_b32_e32 v23, v2
	v_mov_b32_e32 v24, v2
	v_mov_b32_e32 v25, v2
	v_mov_b32_e32 v26, v2
	v_mov_b32_e32 v27, v2
	v_mov_b32_e32 v28, v2
	v_mov_b32_e32 v29, v2
	v_mov_b32_e32 v30, v2
	v_mov_b32_e32 v31, v2
	v_mov_b32_e32 v32, v2
	v_mov_b32_e32 v33, v2
	v_mov_b32_e32 v34, v2
	v_mov_b32_e32 v35, v2
	v_mov_b32_e32 v36, v2
	v_mov_b32_e32 v37, v2
	v_mov_b32_e32 v38, v2
	v_mov_b32_e32 v39, v2
	v_mov_b32_e32 v40, v2
	v_mov_b32_e32 v41, v2
	v_mov_b32_e32 v42, v2
	v_mov_b32_e32 v43, v2
	v_mov_b32_e32 v44, v2
	v_mov_b32_e32 v45, v2
	v_mov_b32_e32 v46, v2
	v_mov_b32_e32 v47, v2
	v_mov_b32_e32 v48, v2
	v_mov_b32_e32 v49, v2
	v_mov_b32_e32 v50, v2
	v_mov_b32_e32 v51, v2
	v_mov_b32_e32 v52, v2
	v_mov_b32_e32 v53, v2
	v_mov_b32_e32 v54, v2
	v_mov_b32_e32 v55, v2
	v_mov_b32_e32 v56, v2
	v_mov_b32_e32 v57, v2
	v_mov_b32_e32 v58, v2
	v_mov_b32_e32 v59, v2
	v_mov_b32_e32 v60, v2
	v_mov_b32_e32 v61, v2
	v_mov_b32_e32 v62, v2
	v_mov_b32_e32 v63, v2
	v_mov_b32_e32 v64, v2
	v_mov_b32_e32 v65, v2
	s_waitcnt lgkmcnt(0)
	s_barrier
	s_waitcnt vmcnt(0)
	v_subrev_u32_e32 v200, s82, v200
	v_add_u32_e32 v200, v200, v180
	v_subrev_u32_e32 v186, s82, v186
	v_add_u32_e32 v186, v186, v180
	v_subrev_u32_e32 v210, s82, v210
	v_add_u32_e32 v210, v210, v180
	v_subrev_u32_e32 v208, s82, v208
	v_add_u32_e32 v208, v208, v180
	v_subrev_u32_e32 v188, s82, v188
	v_add_u32_e32 v188, v188, v180
	v_subrev_u32_e32 v206, s82, v206
	v_add_u32_e32 v206, v206, v180
	v_subrev_u32_e32 v204, s82, v204
	v_add_u32_e32 v204, v204, v180
	v_subrev_u32_e32 v190, s82, v190
	v_add_u32_e32 v190, v190, v180
	v_subrev_u32_e32 v202, s82, v202
	v_add_u32_e32 v202, v202, v180
	v_subrev_u32_e32 v198, s82, v198
	v_add_u32_e32 v198, v198, v180
	v_subrev_u32_e32 v192, s82, v192
	v_add_u32_e32 v192, v192, v180
	v_subrev_u32_e32 v196, s82, v196
	v_add_u32_e32 v196, v196, v180
	s_add_u32 s84, s82, 0xa380000
	s_addc_u32 s85, s83, 0
	s_mov_b32 s86, s82
	s_mov_b32 s87, s83
	s_branch .LBB0_675

.LBB0_674:
	ds_read_b128 v[162:165], v233 offset:55296
	ds_read_b128 v[166:169], v232 offset:36864
	ds_read_b128 v[234:237], v233 offset:59904
	s_mov_b64 s[22:23], 0x200
	s_add_i32 s14, s14, 2
	v_lshl_add_u64 v[194:195], v[194:195], 0, s[22:23]
	s_waitcnt lgkmcnt(1)
	v_mfma_f32_32x32x16_bf16 v[50:65], v[162:165], v[166:169], v[50:65]
	s_add_u32 s84, s84, s16
	s_addc_u32 s85, s85, s17
	s_add_u32 s86, s86, s16
	s_addc_u32 s87, s87, s17
	s_waitcnt lgkmcnt(0)
	v_mfma_f32_32x32x16_bf16 v[34:49], v[234:237], v[166:169], v[34:49]
	ds_read_b128 v[166:169], v232 offset:41472
	s_andn2_b64 vcc, exec, s[2:3]
	s_waitcnt lgkmcnt(0)
	v_mfma_f32_32x32x16_bf16 v[18:33], v[162:165], v[166:169], v[18:33]
	v_mfma_f32_32x32x16_bf16 v[2:17], v[234:237], v[166:169], v[2:17]
	ds_read_b128 v[162:165], v233 offset:55328
	ds_read_b128 v[166:169], v232 offset:36896
	ds_read_b128 v[234:237], v233 offset:59936
	s_waitcnt lgkmcnt(1)
	v_mfma_f32_32x32x16_bf16 v[50:65], v[162:165], v[166:169], v[50:65]
	s_waitcnt lgkmcnt(0)
	v_mfma_f32_32x32x16_bf16 v[34:49], v[234:237], v[166:169], v[34:49]
	ds_read_b128 v[166:169], v232 offset:41504
	s_waitcnt lgkmcnt(0)
	v_mfma_f32_32x32x16_bf16 v[18:33], v[162:165], v[166:169], v[18:33]
	v_mfma_f32_32x32x16_bf16 v[2:17], v[234:237], v[166:169], v[2:17]
	ds_read_b128 v[162:165], v233 offset:55360
	ds_read_b128 v[166:169], v232 offset:36928
	ds_read_b128 v[234:237], v233 offset:59968
	s_waitcnt lgkmcnt(1)
	v_mfma_f32_32x32x16_bf16 v[50:65], v[162:165], v[166:169], v[50:65]
	s_waitcnt lgkmcnt(0)
	v_mfma_f32_32x32x16_bf16 v[34:49], v[234:237], v[166:169], v[34:49]
	ds_read_b128 v[166:169], v232 offset:41536
	s_waitcnt lgkmcnt(0)
	v_mfma_f32_32x32x16_bf16 v[18:33], v[162:165], v[166:169], v[18:33]
	v_mfma_f32_32x32x16_bf16 v[2:17], v[234:237], v[166:169], v[2:17]
	ds_read_b128 v[162:165], v233 offset:55392
	ds_read_b128 v[166:169], v232 offset:36960
	ds_read_b128 v[234:237], v233 offset:60000
	ds_read_b128 v[238:241], v232 offset:41568
	s_waitcnt lgkmcnt(0)
	s_barrier
	v_mfma_f32_32x32x16_bf16 v[50:65], v[162:165], v[166:169], v[50:65]
	v_mfma_f32_32x32x16_bf16 v[34:49], v[234:237], v[166:169], v[34:49]
	v_mfma_f32_32x32x16_bf16 v[18:33], v[162:165], v[238:241], v[18:33]
	v_mfma_f32_32x32x16_bf16 v[2:17], v[234:237], v[238:241], v[2:17]
	s_cbranch_vccz .LBB0_621
.LBB0_675:
	s_waitcnt vmcnt(8)
	v_lshlrev_b32_e32 v234, 16, v66
	v_and_b32_e32 v235, 0xffff0000, v66
	v_lshlrev_b32_e32 v236, 16, v70
	v_and_b32_e32 v237, 0xffff0000, v70
	v_pk_add_f32 v[236:237], v[236:237], v[234:235] neg_lo:[0,1] neg_hi:[0,1]
	v_lshlrev_b32_e32 v238, 16, v71
	v_and_b32_e32 v239, 0xffff0000, v71
	v_lshlrev_b32_e32 v240, 16, v73
	v_and_b32_e32 v241, 0xffff0000, v73
	s_cmp_gt_u32 s14, 12
	v_pk_fma_f32 v[234:235], v[236:237], v[250:251], v[234:235]
	v_lshlrev_b32_e32 v236, 16, v67
	v_and_b32_e32 v237, 0xffff0000, v67
	v_pk_add_f32 v[238:239], v[238:239], v[236:237] neg_lo:[0,1] neg_hi:[0,1]
	v_cvt_pk_bf16_f32 v234, v234, v235
	v_pk_fma_f32 v[236:237], v[238:239], v[252:253], v[236:237]
	v_lshlrev_b32_e32 v238, 16, v72
	v_cvt_pk_bf16_f32 v235, v236, v237
	v_lshlrev_b32_e32 v236, 16, v68
	v_and_b32_e32 v237, 0xffff0000, v68
	v_and_b32_e32 v239, 0xffff0000, v72
	v_pk_add_f32 v[238:239], v[238:239], v[236:237] neg_lo:[0,1] neg_hi:[0,1]
	s_nop 0
	v_pk_fma_f32 v[236:237], v[238:239], v[246:247], v[236:237]
	v_lshlrev_b32_e32 v238, 16, v69
	v_and_b32_e32 v239, 0xffff0000, v69
	v_pk_add_f32 v[240:241], v[240:241], v[238:239] neg_lo:[0,1] neg_hi:[0,1]
	v_cvt_pk_bf16_f32 v236, v236, v237
	v_pk_fma_f32 v[238:239], v[240:241], v[248:249], v[238:239]
	v_lshlrev_b32_e32 v240, 16, v85
	v_cvt_pk_bf16_f32 v237, v238, v239
	ds_write_b128 v213, v[234:237] offset:36864
	ds_write_b128 v213, v[74:77] offset:55296
	v_lshlrev_b32_e32 v234, 16, v78
	v_and_b32_e32 v235, 0xffff0000, v78
	v_lshlrev_b32_e32 v236, 16, v82
	v_and_b32_e32 v237, 0xffff0000, v82
	v_pk_add_f32 v[236:237], v[236:237], v[234:235] neg_lo:[0,1] neg_hi:[0,1]
	v_lshlrev_b32_e32 v238, 16, v83
	v_pk_fma_f32 v[234:235], v[236:237], v[250:251], v[234:235]
	v_lshlrev_b32_e32 v236, 16, v79
	v_and_b32_e32 v237, 0xffff0000, v79
	v_and_b32_e32 v239, 0xffff0000, v83
	v_pk_add_f32 v[238:239], v[238:239], v[236:237] neg_lo:[0,1] neg_hi:[0,1]
	v_cvt_pk_bf16_f32 v234, v234, v235
	v_pk_fma_f32 v[236:237], v[238:239], v[252:253], v[236:237]
	v_lshlrev_b32_e32 v238, 16, v84
	v_cvt_pk_bf16_f32 v235, v236, v237
	v_lshlrev_b32_e32 v236, 16, v80
	v_and_b32_e32 v237, 0xffff0000, v80
	v_and_b32_e32 v239, 0xffff0000, v84
	v_pk_add_f32 v[238:239], v[238:239], v[236:237] neg_lo:[0,1] neg_hi:[0,1]
	v_and_b32_e32 v241, 0xffff0000, v85
	v_pk_fma_f32 v[236:237], v[238:239], v[246:247], v[236:237]
	v_lshlrev_b32_e32 v238, 16, v81
	v_and_b32_e32 v239, 0xffff0000, v81
	v_pk_add_f32 v[240:241], v[240:241], v[238:239] neg_lo:[0,1] neg_hi:[0,1]
	v_cvt_pk_bf16_f32 v236, v236, v237
	v_pk_fma_f32 v[238:239], v[240:241], v[248:249], v[238:239]
	v_lshlrev_b32_e32 v240, 16, v101
	v_cvt_pk_bf16_f32 v237, v238, v239
	ds_write_b128 v213, v[234:237] offset:41472
	ds_write_b128 v213, v[86:89] offset:59904
	v_lshlrev_b32_e32 v234, 16, v94
	v_and_b32_e32 v235, 0xffff0000, v94
	v_lshlrev_b32_e32 v236, 16, v98
	v_and_b32_e32 v237, 0xffff0000, v98
	v_pk_add_f32 v[236:237], v[236:237], v[234:235] neg_lo:[0,1] neg_hi:[0,1]
	v_lshlrev_b32_e32 v238, 16, v99
	v_pk_fma_f32 v[234:235], v[236:237], v[250:251], v[234:235]
	v_lshlrev_b32_e32 v236, 16, v95
	v_and_b32_e32 v237, 0xffff0000, v95
	v_and_b32_e32 v239, 0xffff0000, v99
	v_pk_add_f32 v[238:239], v[238:239], v[236:237] neg_lo:[0,1] neg_hi:[0,1]
	v_cvt_pk_bf16_f32 v234, v234, v235
	v_pk_fma_f32 v[236:237], v[238:239], v[252:253], v[236:237]
	v_lshlrev_b32_e32 v238, 16, v100
	v_cvt_pk_bf16_f32 v235, v236, v237
	v_lshlrev_b32_e32 v236, 16, v96
	v_and_b32_e32 v237, 0xffff0000, v96
	v_and_b32_e32 v239, 0xffff0000, v100
	v_pk_add_f32 v[238:239], v[238:239], v[236:237] neg_lo:[0,1] neg_hi:[0,1]
	v_and_b32_e32 v241, 0xffff0000, v101
	v_pk_fma_f32 v[236:237], v[238:239], v[246:247], v[236:237]
	v_lshlrev_b32_e32 v238, 16, v97
	v_and_b32_e32 v239, 0xffff0000, v97
	v_pk_add_f32 v[240:241], v[240:241], v[238:239] neg_lo:[0,1] neg_hi:[0,1]
	v_cvt_pk_bf16_f32 v236, v236, v237
	v_pk_fma_f32 v[238:239], v[240:241], v[248:249], v[238:239]
	s_nop 0
	v_cvt_pk_bf16_f32 v237, v238, v239
	ds_write_b128 v213, v[234:237] offset:46080
	ds_write_b128 v213, v[90:93] offset:64512
	v_lshlrev_b32_e32 v234, 16, v102
	v_and_b32_e32 v235, 0xffff0000, v102
	v_lshlrev_b32_e32 v236, 16, v106
	v_and_b32_e32 v237, 0xffff0000, v106
	v_pk_add_f32 v[236:237], v[236:237], v[234:235] neg_lo:[0,1] neg_hi:[0,1]
	s_nop 0
	v_pk_fma_f32 v[166:167], v[236:237], v[250:251], v[234:235]
	v_lshlrev_b32_e32 v234, 16, v103
	v_and_b32_e32 v235, 0xffff0000, v103
	v_lshlrev_b32_e32 v236, 16, v107
	v_and_b32_e32 v237, 0xffff0000, v107
	v_pk_add_f32 v[236:237], v[236:237], v[234:235] neg_lo:[0,1] neg_hi:[0,1]
	v_cvt_pk_bf16_f32 v166, v166, v167
	v_pk_fma_f32 v[168:169], v[236:237], v[252:253], v[234:235]
	v_lshlrev_b32_e32 v234, 16, v108
	v_cvt_pk_bf16_f32 v167, v168, v169
	v_lshlrev_b32_e32 v168, 16, v104
	v_and_b32_e32 v169, 0xffff0000, v104
	v_and_b32_e32 v235, 0xffff0000, v108
	v_pk_add_f32 v[234:235], v[234:235], v[168:169] neg_lo:[0,1] neg_hi:[0,1]
	s_nop 0
	v_pk_fma_f32 v[162:163], v[234:235], v[246:247], v[168:169]
	v_lshlrev_b32_e32 v234, 16, v109
	v_cvt_pk_bf16_f32 v168, v162, v163
	v_lshlrev_b32_e32 v162, 16, v105
	v_and_b32_e32 v163, 0xffff0000, v105
	v_and_b32_e32 v235, 0xffff0000, v109
	v_pk_add_f32 v[234:235], v[234:235], v[162:163] neg_lo:[0,1] neg_hi:[0,1]
	s_nop 0
	v_pk_fma_f32 v[162:163], v[234:235], v[248:249], v[162:163]
	s_nop 0
	v_cvt_pk_bf16_f32 v169, v162, v163
	ds_write_b128 v213, v[166:169] offset:50688
	ds_write_b128 v214, v[110:113] offset:13824
	s_cbranch_scc1 .LBB0_683
	global_load_dwordx4 v[246:249], v[194:195], off offset:256
	global_load_dwordx4 v[250:253], v[194:195], off offset:240
	s_nop 0
	global_load_dwordx4 v[66:69], v200, s[84:85] offset:384
	v_mov_b32_e32 v92, 0
	global_load_dwordx4 v[70:73], v186, s[86:87] offset:384
	v_mov_b32_e32 v93, v172
	global_load_dwordx4 v[74:77], v210, s[86:87] offset:-128
	v_mov_b64_e32 v[88:89], v[92:93]
	global_load_dwordx4 v[78:81], v208, s[84:85] offset:384
	v_mov_b64_e32 v[86:87], v[92:93]
	global_load_dwordx4 v[82:85], v188, s[86:87] offset:384
	s_and_saveexec_b64 s[2:3], s[0:1]
	s_cbranch_execz .LBB0_678
	global_load_dwordx4 v[86:89], v206, s[86:87] offset:-128
.LBB0_678:
	s_or_b64 exec, exec, s[2:3]
	s_nop 1
	global_load_dwordx4 v[94:97], v204, s[84:85] offset:384
	global_load_dwordx4 v[98:101], v190, s[86:87] offset:384
	v_mov_b64_e32 v[90:91], v[92:93]
	s_and_saveexec_b64 s[2:3], s[4:5]
	s_cbranch_execz .LBB0_680
	global_load_dwordx4 v[90:93], v202, s[86:87] offset:-128
.LBB0_680:
	s_or_b64 exec, exec, s[2:3]
	s_nop 0
	global_load_dwordx4 v[102:105], v198, s[84:85] offset:384
	v_mov_b32_e32 v111, 0
	global_load_dwordx4 v[106:109], v192, s[86:87] offset:384
	v_mov_b32_e32 v110, 0
	v_mov_b32_e32 v113, 0
	v_mov_b32_e32 v112, 0
	s_and_saveexec_b64 s[2:3], s[6:7]
	s_cbranch_execz .LBB0_682
	global_load_dwordx4 v[110:113], v196, s[86:87] offset:-128

.LBB0_683:
	ds_read_b128 v[162:165], v233 offset:18432
	ds_read_b128 v[166:169], v232
	ds_read_b128 v[234:237], v233 offset:23040
	s_cmp_gt_u32 s14, 13
	s_cselect_b64 s[2:3], -1, 0
	s_and_b64 vcc, exec, s[2:3]
	s_waitcnt lgkmcnt(1)
	v_mfma_f32_32x32x16_bf16 v[50:65], v[162:165], v[166:169], v[50:65]
	s_waitcnt lgkmcnt(0)
	v_mfma_f32_32x32x16_bf16 v[34:49], v[234:237], v[166:169], v[34:49]
	ds_read_b128 v[166:169], v232 offset:4608
	s_waitcnt lgkmcnt(0)
	v_mfma_f32_32x32x16_bf16 v[18:33], v[162:165], v[166:169], v[18:33]
	v_mfma_f32_32x32x16_bf16 v[2:17], v[234:237], v[166:169], v[2:17]
	ds_read_b128 v[162:165], v233 offset:18464
	ds_read_b128 v[166:169], v232 offset:32
	ds_read_b128 v[234:237], v233 offset:23072
	s_waitcnt lgkmcnt(1)
	v_mfma_f32_32x32x16_bf16 v[50:65], v[162:165], v[166:169], v[50:65]
	s_waitcnt lgkmcnt(0)
	v_mfma_f32_32x32x16_bf16 v[34:49], v[234:237], v[166:169], v[34:49]
	ds_read_b128 v[166:169], v232 offset:4640
	s_waitcnt lgkmcnt(0)
	v_mfma_f32_32x32x16_bf16 v[18:33], v[162:165], v[166:169], v[18:33]
	v_mfma_f32_32x32x16_bf16 v[2:17], v[234:237], v[166:169], v[2:17]
	ds_read_b128 v[162:165], v233 offset:18496
	ds_read_b128 v[166:169], v232 offset:64
	ds_read_b128 v[234:237], v233 offset:23104
	s_waitcnt lgkmcnt(1)
	v_mfma_f32_32x32x16_bf16 v[50:65], v[162:165], v[166:169], v[50:65]
	s_waitcnt lgkmcnt(0)
	v_mfma_f32_32x32x16_bf16 v[34:49], v[234:237], v[166:169], v[34:49]
	ds_read_b128 v[166:169], v232 offset:4672
	s_waitcnt lgkmcnt(0)
	v_mfma_f32_32x32x16_bf16 v[18:33], v[162:165], v[166:169], v[18:33]
	v_mfma_f32_32x32x16_bf16 v[2:17], v[234:237], v[166:169], v[2:17]
	ds_read_b128 v[162:165], v233 offset:18528
	ds_read_b128 v[166:169], v232 offset:96
	ds_read_b128 v[234:237], v233 offset:23136
	s_waitcnt lgkmcnt(1)
	v_mfma_f32_32x32x16_bf16 v[50:65], v[162:165], v[166:169], v[50:65]
	s_waitcnt lgkmcnt(0)
	v_mfma_f32_32x32x16_bf16 v[34:49], v[234:237], v[166:169], v[34:49]
	ds_read_b128 v[166:169], v232 offset:4704
	s_waitcnt lgkmcnt(0)
	s_barrier
	v_mfma_f32_32x32x16_bf16 v[18:33], v[162:165], v[166:169], v[18:33]
	v_mfma_f32_32x32x16_bf16 v[2:17], v[234:237], v[166:169], v[2:17]
	s_cbranch_vccnz .LBB0_674
	s_waitcnt vmcnt(8)
	v_lshlrev_b32_e32 v234, 16, v114
	v_and_b32_e32 v235, 0xffff0000, v114
	v_lshlrev_b32_e32 v236, 16, v118
	v_and_b32_e32 v237, 0xffff0000, v118
	v_pk_add_f32 v[236:237], v[236:237], v[234:235] neg_lo:[0,1] neg_hi:[0,1]
	v_lshlrev_b32_e32 v238, 16, v119
	v_and_b32_e32 v239, 0xffff0000, v119
	v_lshlrev_b32_e32 v240, 16, v121
	v_and_b32_e32 v241, 0xffff0000, v121
	s_cmp_gt_u32 s14, 11
	v_pk_fma_f32 v[234:235], v[236:237], v[250:251], v[234:235]
	v_lshlrev_b32_e32 v236, 16, v115
	v_and_b32_e32 v237, 0xffff0000, v115
	v_pk_add_f32 v[238:239], v[238:239], v[236:237] neg_lo:[0,1] neg_hi:[0,1]
	v_cvt_pk_bf16_f32 v234, v234, v235
	v_pk_fma_f32 v[236:237], v[238:239], v[252:253], v[236:237]
	v_lshlrev_b32_e32 v238, 16, v120
	v_cvt_pk_bf16_f32 v235, v236, v237
	v_lshlrev_b32_e32 v236, 16, v116
	v_and_b32_e32 v237, 0xffff0000, v116
	v_and_b32_e32 v239, 0xffff0000, v120
	v_pk_add_f32 v[238:239], v[238:239], v[236:237] neg_lo:[0,1] neg_hi:[0,1]
	s_nop 0
	v_pk_fma_f32 v[236:237], v[238:239], v[246:247], v[236:237]
	v_lshlrev_b32_e32 v238, 16, v117
	v_and_b32_e32 v239, 0xffff0000, v117
	v_pk_add_f32 v[240:241], v[240:241], v[238:239] neg_lo:[0,1] neg_hi:[0,1]
	v_cvt_pk_bf16_f32 v236, v236, v237
	v_pk_fma_f32 v[238:239], v[240:241], v[248:249], v[238:239]
	v_lshlrev_b32_e32 v240, 16, v133
	v_cvt_pk_bf16_f32 v237, v238, v239
	ds_write_b128 v213, v[234:237]
	ds_write_b128 v213, v[122:125] offset:18432
	v_lshlrev_b32_e32 v234, 16, v126
	v_and_b32_e32 v235, 0xffff0000, v126
	v_lshlrev_b32_e32 v236, 16, v130
	v_and_b32_e32 v237, 0xffff0000, v130
	v_pk_add_f32 v[236:237], v[236:237], v[234:235] neg_lo:[0,1] neg_hi:[0,1]
	v_lshlrev_b32_e32 v238, 16, v131
	v_pk_fma_f32 v[234:235], v[236:237], v[250:251], v[234:235]
	v_lshlrev_b32_e32 v236, 16, v127
	v_and_b32_e32 v237, 0xffff0000, v127
	v_and_b32_e32 v239, 0xffff0000, v131
	v_pk_add_f32 v[238:239], v[238:239], v[236:237] neg_lo:[0,1] neg_hi:[0,1]
	v_cvt_pk_bf16_f32 v234, v234, v235
	v_pk_fma_f32 v[236:237], v[238:239], v[252:253], v[236:237]
	v_lshlrev_b32_e32 v238, 16, v132
	v_cvt_pk_bf16_f32 v235, v236, v237
	v_lshlrev_b32_e32 v236, 16, v128
	v_and_b32_e32 v237, 0xffff0000, v128
	v_and_b32_e32 v239, 0xffff0000, v132
	v_pk_add_f32 v[238:239], v[238:239], v[236:237] neg_lo:[0,1] neg_hi:[0,1]
	v_and_b32_e32 v241, 0xffff0000, v133
	v_pk_fma_f32 v[236:237], v[238:239], v[246:247], v[236:237]
	v_lshlrev_b32_e32 v238, 16, v129
	v_and_b32_e32 v239, 0xffff0000, v129
	v_pk_add_f32 v[240:241], v[240:241], v[238:239] neg_lo:[0,1] neg_hi:[0,1]
	v_cvt_pk_bf16_f32 v236, v236, v237
	v_pk_fma_f32 v[238:239], v[240:241], v[248:249], v[238:239]
	v_lshlrev_b32_e32 v240, 16, v149
	v_cvt_pk_bf16_f32 v237, v238, v239
	ds_write_b128 v213, v[234:237] offset:4608
	ds_write_b128 v213, v[134:137] offset:23040
	v_lshlrev_b32_e32 v234, 16, v142
	v_and_b32_e32 v235, 0xffff0000, v142
	v_lshlrev_b32_e32 v236, 16, v146
	v_and_b32_e32 v237, 0xffff0000, v146
	v_pk_add_f32 v[236:237], v[236:237], v[234:235] neg_lo:[0,1] neg_hi:[0,1]
	v_lshlrev_b32_e32 v238, 16, v147
	v_pk_fma_f32 v[234:235], v[236:237], v[250:251], v[234:235]
	v_lshlrev_b32_e32 v236, 16, v143
	v_and_b32_e32 v237, 0xffff0000, v143
	v_and_b32_e32 v239, 0xffff0000, v147
	v_pk_add_f32 v[238:239], v[238:239], v[236:237] neg_lo:[0,1] neg_hi:[0,1]
	v_cvt_pk_bf16_f32 v234, v234, v235
	v_pk_fma_f32 v[236:237], v[238:239], v[252:253], v[236:237]
	v_lshlrev_b32_e32 v238, 16, v148
	v_cvt_pk_bf16_f32 v235, v236, v237
	v_lshlrev_b32_e32 v236, 16, v144
	v_and_b32_e32 v237, 0xffff0000, v144
	v_and_b32_e32 v239, 0xffff0000, v148
	v_pk_add_f32 v[238:239], v[238:239], v[236:237] neg_lo:[0,1] neg_hi:[0,1]
	v_and_b32_e32 v241, 0xffff0000, v149
	v_pk_fma_f32 v[236:237], v[238:239], v[246:247], v[236:237]
	v_lshlrev_b32_e32 v238, 16, v145
	v_and_b32_e32 v239, 0xffff0000, v145
	v_pk_add_f32 v[240:241], v[240:241], v[238:239] neg_lo:[0,1] neg_hi:[0,1]
	v_cvt_pk_bf16_f32 v236, v236, v237
	v_pk_fma_f32 v[238:239], v[240:241], v[248:249], v[238:239]
	s_nop 0
	v_cvt_pk_bf16_f32 v237, v238, v239
	ds_write_b128 v213, v[234:237] offset:9216
	ds_write_b128 v213, v[138:141] offset:27648
	v_lshlrev_b32_e32 v234, 16, v150
	v_and_b32_e32 v235, 0xffff0000, v150
	v_lshlrev_b32_e32 v236, 16, v154
	v_and_b32_e32 v237, 0xffff0000, v154
	v_pk_add_f32 v[236:237], v[236:237], v[234:235] neg_lo:[0,1] neg_hi:[0,1]
	s_nop 0
	v_pk_fma_f32 v[166:167], v[236:237], v[250:251], v[234:235]
	v_lshlrev_b32_e32 v234, 16, v151
	v_and_b32_e32 v235, 0xffff0000, v151
	v_lshlrev_b32_e32 v236, 16, v155
	v_and_b32_e32 v237, 0xffff0000, v155
	v_pk_add_f32 v[236:237], v[236:237], v[234:235] neg_lo:[0,1] neg_hi:[0,1]
	v_cvt_pk_bf16_f32 v166, v166, v167
	v_pk_fma_f32 v[168:169], v[236:237], v[252:253], v[234:235]
	v_lshlrev_b32_e32 v234, 16, v156
	v_cvt_pk_bf16_f32 v167, v168, v169
	v_lshlrev_b32_e32 v168, 16, v152
	v_and_b32_e32 v169, 0xffff0000, v152
	v_and_b32_e32 v235, 0xffff0000, v156
	v_pk_add_f32 v[234:235], v[234:235], v[168:169] neg_lo:[0,1] neg_hi:[0,1]
	s_nop 0
	v_pk_fma_f32 v[162:163], v[234:235], v[246:247], v[168:169]
	v_lshlrev_b32_e32 v234, 16, v157
	v_cvt_pk_bf16_f32 v168, v162, v163
	v_lshlrev_b32_e32 v162, 16, v153
	v_and_b32_e32 v163, 0xffff0000, v153
	v_and_b32_e32 v235, 0xffff0000, v157
	v_pk_add_f32 v[234:235], v[234:235], v[162:163] neg_lo:[0,1] neg_hi:[0,1]
	s_nop 0
	v_pk_fma_f32 v[162:163], v[234:235], v[248:249], v[162:163]
	s_nop 0
	v_cvt_pk_bf16_f32 v169, v162, v163
	ds_write_b128 v213, v[166:169] offset:13824
	ds_write_b128 v213, v[158:161] offset:32256
	global_load_dwordx4 v[246:249], v[194:195], off offset:512
	global_load_dwordx4 v[250:253], v[194:195], off offset:496
	s_cbranch_scc1 .Lmixpf_b_last
	s_nop 0
	global_load_dwordx4 v[114:117], v200, s[84:85] offset:512
	v_mov_b32_e32 v140, 0
	global_load_dwordx4 v[118:121], v186, s[86:87] offset:512
	v_mov_b32_e32 v141, v172
	global_load_dwordx4 v[122:125], v210, s[86:87]
	v_mov_b64_e32 v[136:137], v[140:141]
	global_load_dwordx4 v[126:129], v208, s[84:85] offset:512
	v_mov_b64_e32 v[134:135], v[140:141]
	global_load_dwordx4 v[130:133], v188, s[86:87] offset:512
	s_and_saveexec_b64 s[22:23], s[0:1]
	s_cbranch_execz .LBB0_687
	global_load_dwordx4 v[134:137], v206, s[86:87]
.LBB0_687:
	s_or_b64 exec, exec, s[22:23]
	s_nop 1
	global_load_dwordx4 v[142:145], v204, s[84:85] offset:512
	global_load_dwordx4 v[146:149], v190, s[86:87] offset:512
	v_mov_b64_e32 v[138:139], v[140:141]
	s_and_saveexec_b64 s[22:23], s[4:5]
	s_cbranch_execz .LBB0_689
	global_load_dwordx4 v[138:141], v202, s[86:87]
.LBB0_689:
	s_or_b64 exec, exec, s[22:23]
	s_nop 0
	global_load_dwordx4 v[150:153], v198, s[84:85] offset:512
	v_mov_b32_e32 v159, 0
	global_load_dwordx4 v[154:157], v192, s[86:87] offset:512
	v_mov_b32_e32 v158, 0
	v_mov_b32_e32 v161, 0
	v_mov_b32_e32 v160, 0
	s_and_saveexec_b64 s[22:23], s[6:7]
	s_cbranch_execz .LBB0_673
	global_load_dwordx4 v[158:161], v196, s[86:87]
	s_branch .LBB0_673
